# v27b + one static s_setprio 1 for waves 0-3 (the heavier half) across the RWKV-7 chunk loop
# baseline (speedup 1.0000x reference)
; #define LAS __attribute__((address_space(3)))
; __device__ __forceinline__ unsigned pk2(float lo, float hi) { const bf2_t r = __builtin_convertvector((f32x2){lo, hi}, bf2_t); unsigned u; __builtin_memcpy(&u, &r, 4); return u; }
; __device__ __forceinline__ float bflo(unsigned u) { return __uint_as_float(u << 16); }
; __device__ __forceinline__ float siluf_(float x) { return x * frcp(1.0f + __expf(-x)); }
; __device__ __forceinline__ void rwkv_chunk_item(const P& p, const Ctx& c, int seg, int w, bool save) {
;     ...
;     const int et = (c.tid >> 4) & 15, eg = c.tid & 15; const int ech = hh * 64 + eg * 4;
;     const f32x4 elg = *(const f32x4*)(p.rw_lnx_g + ech), elb = *(const f32x4*)(p.rw_lnx_b + ech);
;     u32x2 e_g = (u32x2){0u, 0u}, e_z = e_g, e_v = e_g; float e_rkr = 0.f;
;     auto eload = [&](int ch) { const size_t rr = (size_t)b * SEGT + ch * 16 + et;
;         e_g = *(const u32x2*)(SG + rr * DMIX + ech); e_v = *(const u32x2*)(SV + rr * DMIX + ech); e_z = *(const u32x2*)(P2 + rr * P2W + 512 + ech); e_rkr = BRKR[(rr * 24 + hh) * 4 + 2]; };
;     auto efinish = [&](int ch) { const f32x4 o4 = *(const LAS f32x4*)(YB + et * 68 + eg * 4);
;         float s1 = (o4[0] + o4[1]) + (o4[2] + o4[3]), s2 = (o4[0] * o4[0] + o4[1] * o4[1]) + (o4[2] * o4[2] + o4[3] * o4[3]);
;         s1 = dpp_add<0xB1>(s1); s2 = dpp_add<0xB1>(s2); s1 = dpp_add<0x4E>(s1); s2 = dpp_add<0x4E>(s2); s1 = dpp_add<0x141>(s1); s2 = dpp_add<0x141>(s2); s1 = dpp_add<0x140>(s1); s2 = dpp_add<0x140>(s2);
;         const float mean = s1 * (1.0f / 64.0f), var = fmaxf(s2 * (1.0f / 64.0f) - mean * mean, 0.f), rs = rsqrtf(var + 64e-5f);
;         const float gg[4] = {bflo(e_g.x), bfhi(e_g.x), bflo(e_g.y), bfhi(e_g.y)}, vv[4] = {bflo(e_v.x), bfhi(e_v.x), bflo(e_v.y), bfhi(e_v.y)}, zz[4] = {bflo(e_z.x), bfhi(e_z.x), bflo(e_z.y), bfhi(e_z.y)};
;         float y[4];
; #pragma unroll
;         for (int j = 0; j < 4; ++j) y[j] = ((o4[j] - mean) * rs * elg[j] + elb[j] + e_rkr * vv[j]) * gg[j] * siluf_(zz[j]);
;         *(u32x2*)(Y + ((size_t)b * SEGT + ch * 16 + et) * DIN + ech) = (u32x2){pk2(y[0], y[1]), pk2(y[2], y[3])}; };
;     __syncthreads();
;     { int t0 = c.tid; asm volatile("" : "+v"(t0)); gload(0, t0); lstore(0, t0); simg(l15c, quadc); }
;     lds_barrier();
;     if (c.wv < 4) gtile(0, l15c, quadc);
;     { int t1 = c.tid; asm volatile("" : "+v"(t1)); gload(1, t1); }
;     const int mtq = c.wv & 3;
.LBB0_885:
	s_or_b64 exec, exec, s[2:3]
	s_lshl_b64 s[2:3], s[78:79], 21
	s_add_u32 s2, s35, s2
	s_addc_u32 s3, s39, s3
	s_add_u32 s54, s2, 0x9700000
	s_addc_u32 s55, s3, 0
	s_lshl_b32 s2, s74, 4
	s_and_b32 s35, s2, 48
	s_lshl_b32 s2, s35, 2
	s_add_i32 s39, s2, 0
	s_add_i32 s40, s40, 0
	s_cmp_gt_i32 s74, 3
	s_cselect_b64 s[56:57], -1, 0
	s_cmp_lt_i32 s74, 4
	s_cselect_b64 s[68:69], -1, 0
	s_cbranch_scc0 .Lrw_prio_skip
	s_setprio 1
.Lrw_prio_skip:
	s_cmp_lt_u32 s72, 64
	s_cselect_b64 s[70:71], -1, 0
	s_ashr_i32 s2, s72, 7
	s_lshr_b32 s3, s72, 2
	s_or_b32 s66, s34, 16
	s_lshl_b32 s67, s2, 4
	s_and_b32 s83, s3, 16
	s_bitcmp1_b32 s72, 6
	s_cselect_b64 s[72:73], -1, 0
	s_lshl_b32 s84, s2, 5
	s_cmp_gt_u32 s74, 1
	s_cselect_b64 s[74:75], -1, 0
	s_add_i32 s85, s85, 2
	s_add_u32 s76, s76, 32
	s_addc_u32 s77, s77, 0
	s_mul_i32 s2, s78, 0x3000
	s_mul_hi_i32 s3, s78, 0x3000
	s_add_u32 s2, s46, s2
	v_bfe_u32 v67, v55, 4, 4
	s_addc_u32 s3, s47, s3
	v_mad_u64_u32 v[24:25], s[2:3], v67, 24, s[2:3]
	v_readlane_b32 s2, v255, 17
	v_and_b32_e32 v2, 63, v55
	v_readlane_b32 s3, v255, 18
	v_mul_u32_u24_e32 v40, 0x44, v2
	v_mul_u32_u24_e32 v80, 0x50, v2
	v_lshl_add_u64 v[32:33], v[24:25], 4, s[2:3]
	s_mul_hi_i32 s2, s78, 0x280000
	s_mul_i32 s3, s78, 0x280000
	v_mul_hi_u32_u24_e32 v2, 0x1400, v67
	v_mul_u32_u24_e32 v24, 0x1400, v67
	v_lshlrev_b64 v[22:23], 1, v[28:29]
	v_or_b32_e32 v25, s2, v2
	v_or_b32_e32 v24, s3, v24
	v_readlane_b32 s2, v255, 19
	v_lshl_add_u64 v[24:25], v[24:25], 0, v[22:23]
	v_readlane_b32 s3, v255, 20
	v_mul_hi_u32_u24_e32 v2, 0xc00, v67
	v_lshrrev_b32_e32 v4, 4, v55
	v_lshl_add_u64 v[34:35], s[2:3], 0, v[24:25]
	s_mul_hi_i32 s2, s78, 0x180000
	s_mul_i32 s3, s78, 0x180000
	v_mul_u32_u24_e32 v24, 0xc00, v67
	v_or_b32_e32 v25, s2, v2
	v_or_b32_e32 v24, s3, v24
	v_lshl_add_u64 v[30:31], s[54:55], 0, v[22:23]
	v_lshl_add_u64 v[22:23], v[24:25], 0, v[22:23]
	v_mov_b32_e32 v38, v5
	v_mov_b32_e32 v39, v5
	v_or_b32_e32 v4, -16, v4
	v_mad_u32_u24 v77, v67, s38, 0
	v_lshlrev_b32_e32 v78, 4, v59
	v_lshl_add_u64 v[36:37], s[94:95], 0, v[22:23]
	s_mov_b32 s86, 0
	v_mov_b32_e32 v2, 0
	v_add_u32_e32 v81, 0, v40
	v_mov_b64_e32 v[40:41], v[38:39]
	v_mov_b64_e32 v[42:43], v[38:39]

; #define LAS __attribute__((address_space(3)))
; __device__ __forceinline__ unsigned pk2(float lo, float hi) { const bf2_t r = __builtin_convertvector((f32x2){lo, hi}, bf2_t); unsigned u; __builtin_memcpy(&u, &r, 4); return u; }
; __device__ __forceinline__ float bflo(unsigned u) { return __uint_as_float(u << 16); }
; __device__ __forceinline__ float bfhi(unsigned u) { return __uint_as_float(u & 0xFFFF0000u); }
; __device__ __forceinline__ float siluf_(float x) { return x * frcp(1.0f + __expf(-x)); }
; __device__ __forceinline__ void lds_barrier() { asm volatile("s_waitcnt lgkmcnt(0)" ::: "memory"); __builtin_amdgcn_s_barrier(); asm volatile("" ::: "memory"); }
; __device__ __forceinline__ void rwkv_chunk_item(const P& p, const Ctx& c, int seg, int w, bool save) {
;     ...
;     auto efinish = [&](int ch) { const f32x4 o4 = *(const LAS f32x4*)(YB + et * 68 + eg * 4);
;         float s1 = (o4[0] + o4[1]) + (o4[2] + o4[3]), s2 = (o4[0] * o4[0] + o4[1] * o4[1]) + (o4[2] * o4[2] + o4[3] * o4[3]);
;         s1 = dpp_add<0xB1>(s1); s2 = dpp_add<0xB1>(s2); s1 = dpp_add<0x4E>(s1); s2 = dpp_add<0x4E>(s2); s1 = dpp_add<0x141>(s1); s2 = dpp_add<0x141>(s2); s1 = dpp_add<0x140>(s1); s2 = dpp_add<0x140>(s2);
;         const float mean = s1 * (1.0f / 64.0f), var = fmaxf(s2 * (1.0f / 64.0f) - mean * mean, 0.f), rs = rsqrtf(var + 64e-5f);
;         const float gg[4] = {bflo(e_g.x), bfhi(e_g.x), bflo(e_g.y), bfhi(e_g.y)}, vv[4] = {bflo(e_v.x), bfhi(e_v.x), bflo(e_v.y), bfhi(e_v.y)}, zz[4] = {bflo(e_z.x), bfhi(e_z.x), bflo(e_z.y), bfhi(e_z.y)};
;         float y[4];
; #pragma unroll
;         for (int j = 0; j < 4; ++j) y[j] = ((o4[j] - mean) * rs * elg[j] + elb[j] + e_rkr * vv[j]) * gg[j] * siluf_(zz[j]);
;         *(u32x2*)(Y + ((size_t)b * SEGT + ch * 16 + et) * DIN + ech) = (u32x2){pk2(y[0], y[1]), pk2(y[2], y[3])}; };
;     ...
;     lds_barrier();
;     if (c.wv < 4) efinish(SEGT / 16 - 1);
.LBB0_935:
	s_setprio 0
	s_waitcnt lgkmcnt(0)
	s_barrier
	s_and_b64 vcc, exec, s[6:7]
	s_cbranch_vccz .LBB0_822
	v_add_u32_e32 v2, v77, v78
	ds_read_b128 v[22:25], v2 offset:60672
	s_mov_b32 s2, 0x3c800000
	s_waitcnt lgkmcnt(0)
	v_mul_f32_e32 v30, v22, v22
	v_mul_f32_e32 v32, v23, v23
	v_mul_f32_e32 v34, v24, v24
	v_mul_f32_e32 v36, v25, v25
	v_mov_b32_e32 v31, v22
	v_mov_b32_e32 v33, v23
	v_mov_b32_e32 v35, v24
	v_mov_b32_e32 v37, v25
	v_pk_add_f32 v[30:31], v[30:31], v[32:33]
	v_pk_add_f32 v[32:33], v[34:35], v[36:37]
	s_waitcnt vmcnt(1)
	v_lshlrev_b32_e32 v36, 16, v46
	v_pk_add_f32 v[30:31], v[30:31], v[32:33]
	v_and_b32_e32 v37, 0xffff0000, v46
	v_lshlrev_b32_e32 v34, 16, v48
	v_mov_b32_dpp v33, v31 quad_perm:[1,0,3,2] row_mask:0xf bank_mask:0xf bound_ctrl:1
	v_mov_b32_dpp v32, v30 quad_perm:[1,0,3,2] row_mask:0xf bank_mask:0xf bound_ctrl:1
	v_pk_add_f32 v[30:31], v[30:31], v[32:33]
	v_and_b32_e32 v35, 0xffff0000, v48
	s_nop 0
	v_mov_b32_dpp v33, v31 quad_perm:[2,3,0,1] row_mask:0xf bank_mask:0xf bound_ctrl:1
	v_mov_b32_dpp v32, v30 quad_perm:[2,3,0,1] row_mask:0xf bank_mask:0xf bound_ctrl:1
	v_pk_add_f32 v[30:31], v[30:31], v[32:33]
	s_nop 1
	v_mov_b32_dpp v33, v31 row_half_mirror row_mask:0xf bank_mask:0xf bound_ctrl:1
	v_mov_b32_dpp v32, v30 row_half_mirror row_mask:0xf bank_mask:0xf bound_ctrl:1
	v_pk_add_f32 v[30:31], v[30:31], v[32:33]
	s_nop 1
	v_mov_b32_dpp v33, v31 row_mirror row_mask:0xf bank_mask:0xf bound_ctrl:1
	v_mov_b32_dpp v32, v30 row_mirror row_mask:0xf bank_mask:0xf bound_ctrl:1
	v_pk_add_f32 v[30:31], v[30:31], v[32:33]
	v_lshlrev_b32_e32 v32, 16, v50
	v_pk_mul_f32 v[30:31], v[30:31], s[2:3] op_sel_hi:[1,0]
	v_and_b32_e32 v33, 0xffff0000, v50
	v_fma_f32 v2, -v31, v31, v30
	v_max_f32_e32 v2, 0, v2
	v_add_f32_e32 v2, 0x3a27c5ac, v2
	v_cmp_gt_f32_e32 vcc, s51, v2
	v_mul_f32_e32 v4, 0x4b800000, v2
	v_pk_add_f32 v[22:23], v[22:23], v[30:31] op_sel:[0,1] neg_lo:[0,1] neg_hi:[0,1]
	v_cndmask_b32_e32 v2, v2, v4, vcc
	v_rsq_f32_e32 v2, v2
	v_pk_add_f32 v[24:25], v[24:25], v[30:31] op_sel:[0,1] neg_lo:[0,1] neg_hi:[0,1]
	v_mul_f32_e32 v4, 0x45800000, v2
	v_cndmask_b32_e32 v2, v2, v4, vcc
	v_mul_f32_e32 v4, 0xbfb8aa3b, v36
	v_exp_f32_e32 v4, v4
	v_pk_mul_f32 v[22:23], v[22:23], v[2:3] op_sel_hi:[1,0]
	v_pk_mul_f32 v[24:25], v[24:25], v[2:3] op_sel_hi:[1,0]
	v_pk_fma_f32 v[14:15], v[14:15], v[22:23], v[18:19]
	v_add_f32_e32 v4, 1.0, v4
	v_rcp_f32_e32 v38, v4
	v_mul_f32_e32 v4, 0xbfb8aa3b, v37
	v_exp_f32_e32 v4, v4
	s_waitcnt vmcnt(0)
	v_pk_fma_f32 v[14:15], v[44:45], v[34:35], v[14:15] op_sel_hi:[0,1,1]
	v_pk_mul_f32 v[14:15], v[14:15], v[32:33]
	v_lshlrev_b32_e32 v32, 16, v47
	v_add_f32_e32 v4, 1.0, v4
	v_and_b32_e32 v33, 0xffff0000, v47
	v_rcp_f32_e32 v39, v4
	v_mul_f32_e32 v4, 0xbfb8aa3b, v32
	v_mul_f32_e32 v2, 0xbfb8aa3b, v33
	v_exp_f32_e32 v4, v4
	v_exp_f32_e32 v2, v2
	v_pk_mul_f32 v[18:19], v[38:39], v[36:37]
	v_lshlrev_b32_e32 v22, 16, v49
	v_add_f32_e32 v4, 1.0, v4
	v_add_f32_e32 v2, 1.0, v2
	v_rcp_f32_e32 v34, v4
	v_rcp_f32_e32 v35, v2
	v_and_b32_e32 v23, 0xffff0000, v49
	v_pk_fma_f32 v[16:17], v[16:17], v[24:25], v[20:21]
	v_pk_mul_f32 v[14:15], v[18:19], v[14:15]
	v_lshlrev_b32_e32 v18, 16, v51
	v_and_b32_e32 v19, 0xffff0000, v51
	v_pk_fma_f32 v[16:17], v[44:45], v[22:23], v[16:17] op_sel_hi:[0,1,1]
	v_pk_mul_f32 v[16:17], v[16:17], v[18:19]
	v_pk_mul_f32 v[18:19], v[34:35], v[32:33]
	v_lshlrev_b32_e32 v4, 12, v67
	v_pk_mul_f32 v[16:17], v[18:19], v[16:17]
	v_cvt_pk_bf16_f32 v14, v14, v15
	v_cvt_pk_bf16_f32 v15, v16, v17
	v_lshl_add_u64 v[16:17], s[54:55], 0, v[4:5]
	v_lshl_add_u64 v[16:17], v[28:29], 1, v[16:17]
	v_add_co_u32_e32 v16, vcc, 0x1f0000, v16
	s_nop 1
	v_addc_co_u32_e32 v17, vcc, 0, v17, vcc
	global_store_dwordx2 v[16:17], v[14:15], off
	s_branch .LBB0_822
